# speedup vs baseline: 1.0037x; 1.0023x over previous
; #define LAS __attribute__((address_space(3)))
; __device__ __forceinline__ unsigned pk_bf16(float lo, float hi) { f32x2 v = {lo, hi}; bf16x2_t b = __builtin_convertvector(v, bf16x2_t); return __builtin_bit_cast(unsigned, b); }
; __device__ __forceinline__ float bf_lo(unsigned w) { return __uint_as_float(w << 16); }
; __device__ __forceinline__ float bf_hi(unsigned w) { return __uint_as_float(w & 0xffff0000u); }
; __device__ __forceinline__ void gmlp_unit(LAS unsigned char* lds, const bf16_t* __restrict__ Zb, const bf16_t* __restrict__ wsp, const float* __restrict__ bsp, bf16_t* __restrict__ mix, int chunk, int g) {
;     ...
;     for (int rr = 0; rr < 16; ++rr) {
;         const int q = wid * 16 + rr;
;         const unsigned w = *((const unsigned*)(Zb + (row0 + q) * NIN0 + 1088 + 1024 + g * 128) + lane);
;         const float a = bf_lo(w), c = bf_hi(w);
;         const float mean = wave_sum(a + c) * (1.0f / 128.0f), da = a - mean, dc = c - mean;
;         const float rstd = 1.0f / sqrtf(wave_sum(da * da + dc * dc) * (1.0f / 128.0f) + EPS);
;         *(LAS unsigned*)(lds + q * VS + lane * 4) = pk_bf16(da * rstd, dc * rstd);
;     }
.Lgm_nopf:
	s_cmp_lg_u32 s40, 0x1a000
	v_add_f32_e32 v5, v3, v2
	v_add_f32_e32 v12, v7, v6
	v_add_f32_e32 v13, v9, v8
	v_add_f32_e32 v14, v11, v10
	v_add_f32_dpp v5, v5, v5 quad_perm:[1,0,3,2] row_mask:0xf bank_mask:0xf
	v_add_f32_dpp v12, v12, v12 quad_perm:[1,0,3,2] row_mask:0xf bank_mask:0xf
	v_add_f32_dpp v13, v13, v13 quad_perm:[1,0,3,2] row_mask:0xf bank_mask:0xf
	v_add_f32_dpp v14, v14, v14 quad_perm:[1,0,3,2] row_mask:0xf bank_mask:0xf
	v_add_f32_dpp v5, v5, v5 quad_perm:[2,3,0,1] row_mask:0xf bank_mask:0xf
	v_add_f32_dpp v12, v12, v12 quad_perm:[2,3,0,1] row_mask:0xf bank_mask:0xf
	v_add_f32_dpp v13, v13, v13 quad_perm:[2,3,0,1] row_mask:0xf bank_mask:0xf
	v_add_f32_dpp v14, v14, v14 quad_perm:[2,3,0,1] row_mask:0xf bank_mask:0xf
	v_add_f32_dpp v5, v5, v5 row_half_mirror row_mask:0xf bank_mask:0xf
	v_add_f32_dpp v12, v12, v12 row_half_mirror row_mask:0xf bank_mask:0xf
	v_add_f32_dpp v13, v13, v13 row_half_mirror row_mask:0xf bank_mask:0xf
	v_add_f32_dpp v14, v14, v14 row_half_mirror row_mask:0xf bank_mask:0xf
	v_add_f32_dpp v5, v5, v5 row_mirror row_mask:0xf bank_mask:0xf
	v_add_f32_dpp v12, v12, v12 row_mirror row_mask:0xf bank_mask:0xf
	v_add_f32_dpp v13, v13, v13 row_mirror row_mask:0xf bank_mask:0xf
	v_add_f32_dpp v14, v14, v14 row_mirror row_mask:0xf bank_mask:0xf
	v_mov_b32_e32 v15, v5
	v_mov_b32_e32 v16, v12
	v_mov_b32_e32 v17, v13
	v_mov_b32_e32 v18, v14
	v_permlane16_swap_b32_e32 v5, v15
	v_permlane16_swap_b32_e32 v12, v16
	v_permlane16_swap_b32_e32 v13, v17
	v_permlane16_swap_b32_e32 v14, v18
	v_add_f32_e32 v5, v5, v15
	v_add_f32_e32 v12, v12, v16
	v_add_f32_e32 v13, v13, v17
	v_add_f32_e32 v14, v14, v18
	v_mov_b32_e32 v15, v5
	v_mov_b32_e32 v16, v12
	v_mov_b32_e32 v17, v13
	v_mov_b32_e32 v18, v14
	v_permlane32_swap_b32_e32 v5, v15
	v_permlane32_swap_b32_e32 v12, v16
	v_permlane32_swap_b32_e32 v13, v17
	v_permlane32_swap_b32_e32 v14, v18
	v_add_f32_e32 v5, v5, v15
	v_add_f32_e32 v15, v12, v16
	v_add_f32_e32 v13, v13, v17
	v_add_f32_e32 v17, v14, v18
	v_mul_f32_e32 v12, 0x3c000000, v5
	v_mul_f32_e32 v14, 0x3c000000, v15
	v_mul_f32_e32 v16, 0x3c000000, v13
	v_pk_add_f32 v[2:3], v[2:3], v[12:13] op_sel_hi:[1,0] neg_lo:[0,1] neg_hi:[0,1]
	v_pk_add_f32 v[6:7], v[6:7], v[14:15] op_sel_hi:[1,0] neg_lo:[0,1] neg_hi:[0,1]
	v_pk_add_f32 v[8:9], v[8:9], v[16:17] op_sel_hi:[1,0] neg_lo:[0,1] neg_hi:[0,1]
	v_pk_mul_f32 v[12:13], v[2:3], v[2:3]
	v_mul_f32_e32 v18, 0x3c000000, v17
	v_pk_mul_f32 v[14:15], v[6:7], v[6:7]
	v_pk_mul_f32 v[16:17], v[8:9], v[8:9]
	v_add_f32_e32 v5, v12, v13
	v_add_f32_e32 v12, v14, v15
	v_add_f32_e32 v13, v16, v17
	v_pk_add_f32 v[10:11], v[10:11], v[18:19] op_sel_hi:[1,0] neg_lo:[0,1] neg_hi:[0,1]
	v_pk_mul_f32 v[18:19], v[10:11], v[10:11]
	v_add_f32_e32 v14, v18, v19
	v_add_f32_dpp v5, v5, v5 quad_perm:[1,0,3,2] row_mask:0xf bank_mask:0xf
	v_add_f32_dpp v12, v12, v12 quad_perm:[1,0,3,2] row_mask:0xf bank_mask:0xf
	v_add_f32_dpp v13, v13, v13 quad_perm:[1,0,3,2] row_mask:0xf bank_mask:0xf
	v_add_f32_dpp v14, v14, v14 quad_perm:[1,0,3,2] row_mask:0xf bank_mask:0xf
	v_add_f32_dpp v5, v5, v5 quad_perm:[2,3,0,1] row_mask:0xf bank_mask:0xf
	v_add_f32_dpp v12, v12, v12 quad_perm:[2,3,0,1] row_mask:0xf bank_mask:0xf
	v_add_f32_dpp v13, v13, v13 quad_perm:[2,3,0,1] row_mask:0xf bank_mask:0xf
	v_add_f32_dpp v14, v14, v14 quad_perm:[2,3,0,1] row_mask:0xf bank_mask:0xf
	v_add_f32_dpp v5, v5, v5 row_half_mirror row_mask:0xf bank_mask:0xf
	v_add_f32_dpp v12, v12, v12 row_half_mirror row_mask:0xf bank_mask:0xf
	v_add_f32_dpp v13, v13, v13 row_half_mirror row_mask:0xf bank_mask:0xf
	v_add_f32_dpp v14, v14, v14 row_half_mirror row_mask:0xf bank_mask:0xf
	v_add_f32_dpp v5, v5, v5 row_mirror row_mask:0xf bank_mask:0xf
	v_add_f32_dpp v12, v12, v12 row_mirror row_mask:0xf bank_mask:0xf
	v_add_f32_dpp v13, v13, v13 row_mirror row_mask:0xf bank_mask:0xf
	v_add_f32_dpp v14, v14, v14 row_mirror row_mask:0xf bank_mask:0xf
	v_mov_b32_e32 v15, v5
	v_mov_b32_e32 v16, v12
	v_mov_b32_e32 v17, v13
	v_mov_b32_e32 v18, v14
	v_permlane16_swap_b32_e32 v5, v15
	v_permlane16_swap_b32_e32 v12, v16
	v_permlane16_swap_b32_e32 v13, v17
	v_permlane16_swap_b32_e32 v14, v18
	v_add_f32_e32 v5, v5, v15
	v_add_f32_e32 v12, v12, v16
	v_add_f32_e32 v13, v13, v17
	v_add_f32_e32 v14, v14, v18
	v_mov_b32_e32 v15, v5
	v_mov_b32_e32 v16, v12
	v_mov_b32_e32 v17, v13
	v_mov_b32_e32 v18, v14
	v_permlane32_swap_b32_e32 v5, v15
	v_permlane32_swap_b32_e32 v12, v16
	v_permlane32_swap_b32_e32 v13, v17
	v_permlane32_swap_b32_e32 v14, v18
	v_add_f32_e32 v5, v5, v15
	v_add_f32_e32 v12, v12, v16
	v_add_f32_e32 v13, v13, v17
	v_add_f32_e32 v14, v14, v18
	v_fmamk_f32 v5, v5, 0x3c000000, v95
	v_fmamk_f32 v12, v12, 0x3c000000, v95
	v_fmamk_f32 v13, v13, 0x3c000000, v95
	v_mul_f32_e32 v15, 0x4f800000, v5
	v_cmp_gt_f32_e64 s[4:5], s58, v5
	v_mul_f32_e32 v16, 0x4f800000, v12
	v_cmp_gt_f32_e32 vcc, s58, v12
	v_mul_f32_e32 v17, 0x4f800000, v13
	v_cmp_gt_f32_e64 s[0:1], s58, v13
	v_cndmask_b32_e64 v5, v5, v15, s[4:5]
	v_cndmask_b32_e32 v12, v12, v16, vcc
	v_cndmask_b32_e64 v13, v13, v17, s[0:1]
	v_sqrt_f32_e32 v15, v5
	v_fmamk_f32 v14, v14, 0x3c000000, v95
	v_sqrt_f32_e32 v16, v12
	v_sqrt_f32_e32 v17, v13
	v_mul_f32_e32 v18, 0x4f800000, v14
	v_cmp_gt_f32_e64 s[2:3], s58, v14
	v_add_u32_e32 v19, -1, v15
	v_add_u32_e32 v20, 1, v15
	v_cndmask_b32_e64 v14, v14, v18, s[2:3]
	v_sqrt_f32_e32 v18, v14
	v_add_u32_e32 v21, -1, v16
	v_add_u32_e32 v23, -1, v17
	v_fma_f32 v27, -v19, v15, v5
	v_add_u32_e32 v22, 1, v16
	v_add_u32_e32 v24, 1, v17
	v_fma_f32 v28, -v20, v15, v5
	v_fma_f32 v29, -v21, v16, v12
	v_fma_f32 v31, -v23, v17, v13
	v_cmp_ge_f32_e64 s[10:11], 0, v27
	v_fma_f32 v30, -v22, v16, v12
; #define LAS __attribute__((address_space(3)))
; __device__ __forceinline__ unsigned pk_bf16(float lo, float hi) { f32x2 v = {lo, hi}; bf16x2_t b = __builtin_convertvector(v, bf16x2_t); return __builtin_bit_cast(unsigned, b); }
; #define MFMA32(a, b, c) __builtin_amdgcn_mfma_f32_32x32x16_bf16((a), (b), (c), 0, 0, 0)
; __device__ __forceinline__ void gmlp_unit(LAS unsigned char* lds, const bf16_t* __restrict__ Zb, const bf16_t* __restrict__ wsp, const float* __restrict__ bsp, bf16_t* __restrict__ mix, int chunk, int g) {
;     ...
;         const float mean = wave_sum(a + c) * (1.0f / 128.0f), da = a - mean, dc = c - mean;
;         const float rstd = 1.0f / sqrtf(wave_sum(da * da + dc * dc) * (1.0f / 128.0f) + EPS);
;         *(LAS unsigned*)(lds + q * VS + lane * 4) = pk_bf16(da * rstd, dc * rstd);
;     }
;     __syncthreads();
;     const int pb = wid >> 1, cb0 = 2 * (wid & 1);
;     f32x16 acc[2];
; #pragma unroll
;     for (int e = 0; e < 16; ++e) { acc[0][e] = 0.f; acc[1][e] = 0.f; }
;     const bf16_t* ap = wsp + (size_t)g * 16384 + (size_t)(32 * pb + r) * 128 + 8 * h;
;     const int vlane = (8 * h + ((lane & 15) >> 2)) * VS + (16 * ((lane >> 4) & 1) + 4 * (lane & 3)) * 2;
; #pragma unroll
;     for (int ks = 0; ks < 8; ++ks) {
;         const bf16x8 af = *(const bf16x8*)(ap + 16 * ks);
; #pragma unroll
;         for (int ci = 0; ci < 2; ++ci) {
;             const LAS unsigned char* vp = lds + vlane + (16 * ks) * VS + (cb0 + ci) * 64;
;             const s16x4 lo = tr_read(vp), hi = tr_read(vp + 4 * VS);
;             const bf16x8 vf = __builtin_shufflevector(lo, hi, 0, 1, 2, 3, 4, 5, 6, 7);
;             acc[ci] = MFMA32(af, vf, acc[ci]);
	v_fma_f32 v32, -v24, v17, v13
	v_cndmask_b32_e64 v15, v15, v19, s[10:11]
	v_cmp_ge_f32_e64 s[10:11], 0, v29
	v_cmp_ge_f32_e64 s[12:13], 0, v31
	v_cmp_lt_f32_e64 s[16:17], 0, v28
	v_add_u32_e32 v25, -1, v18
	v_cndmask_b32_e64 v16, v16, v21, s[10:11]
	v_cmp_lt_f32_e64 s[10:11], 0, v30
	v_cndmask_b32_e64 v17, v17, v23, s[12:13]
	v_cmp_lt_f32_e64 s[12:13], 0, v32
	v_cndmask_b32_e64 v15, v15, v20, s[16:17]
	v_add_u32_e32 v26, 1, v18
	v_fma_f32 v33, -v25, v18, v14
	v_cndmask_b32_e64 v16, v16, v22, s[10:11]
	v_cndmask_b32_e64 v17, v17, v24, s[12:13]
	v_mul_f32_e32 v19, 0x37800000, v15
	v_fma_f32 v34, -v26, v18, v14
	v_cmp_ge_f32_e64 s[14:15], 0, v33
	v_mul_f32_e32 v20, 0x37800000, v16
	v_mul_f32_e32 v21, 0x37800000, v17
	v_cndmask_b32_e64 v15, v15, v19, s[4:5]
	v_cmp_class_f32_e64 s[4:5], v5, v96
	v_cndmask_b32_e64 v18, v18, v25, s[14:15]
	v_cmp_lt_f32_e64 s[14:15], 0, v34
	v_cndmask_b32_e32 v16, v16, v20, vcc
	v_cmp_class_f32_e32 vcc, v12, v96
	v_cndmask_b32_e64 v17, v17, v21, s[0:1]
	v_cmp_class_f32_e64 s[0:1], v13, v96
	v_cndmask_b32_e64 v5, v15, v5, s[4:5]
	v_cndmask_b32_e64 v18, v18, v26, s[14:15]
	v_cndmask_b32_e32 v15, v16, v12, vcc
	v_cndmask_b32_e64 v13, v17, v13, s[0:1]
	v_div_scale_f32 v12, s[0:1], v5, v5, 1.0
	v_mul_f32_e32 v22, 0x37800000, v18
	v_div_scale_f32 v17, s[0:1], v15, v15, 1.0
	v_rcp_f32_e32 v23, v12
	v_cndmask_b32_e64 v18, v18, v22, s[2:3]
	v_cmp_class_f32_e64 s[2:3], v14, v96
	v_rcp_f32_e32 v24, v17
	v_fma_f32 v27, -v12, v23, 1.0
	v_cndmask_b32_e64 v14, v18, v14, s[2:3]
	v_div_scale_f32 v19, s[2:3], v13, v13, 1.0
	v_div_scale_f32 v21, s[4:5], v14, v14, 1.0
	v_rcp_f32_e32 v25, v19
	v_rcp_f32_e32 v26, v21
	v_div_scale_f32 v16, vcc, 1.0, v5, 1.0
	v_fma_f32 v28, -v17, v24, 1.0
	v_fmac_f32_e32 v23, v27, v23
	v_div_scale_f32 v18, s[0:1], 1.0, v15, 1.0
	v_fmac_f32_e32 v24, v28, v24
	v_mul_f32_e32 v27, v16, v23
	v_fma_f32 v29, -v19, v25, 1.0
	v_mul_f32_e32 v28, v18, v24
	v_fma_f32 v31, -v12, v27, v16
	v_div_scale_f32 v20, s[2:3], 1.0, v13, 1.0
	v_fma_f32 v30, -v21, v26, 1.0
	v_fmac_f32_e32 v25, v29, v25
	v_fma_f32 v32, -v17, v28, v18
	v_fmac_f32_e32 v27, v31, v23
	v_div_scale_f32 v22, s[4:5], 1.0, v14, 1.0
	v_fmac_f32_e32 v26, v30, v26
	v_mul_f32_e32 v29, v20, v25
	v_fmac_f32_e32 v28, v32, v24
	v_fma_f32 v12, -v12, v27, v16
	v_mul_f32_e32 v30, v22, v26
	v_fma_f32 v33, -v19, v29, v20
	v_fma_f32 v16, -v17, v28, v18
	v_div_fmas_f32 v12, v12, v23, v27
	s_mov_b64 vcc, s[0:1]
	v_fma_f32 v34, -v21, v30, v22
	v_fmac_f32_e32 v29, v33, v25
	v_div_fixup_f32 v12, v12, v5, 1.0
	v_div_fmas_f32 v5, v16, v24, v28
	v_fmac_f32_e32 v30, v34, v26
	v_fma_f32 v17, -v19, v29, v20
	v_pk_mul_f32 v[2:3], v[2:3], v[12:13] op_sel_hi:[1,0]
	v_div_fixup_f32 v12, v5, v15, 1.0
	s_mov_b64 vcc, s[2:3]
	v_fma_f32 v18, -v21, v30, v22
	v_div_fmas_f32 v5, v17, v25, v29
	v_cvt_pk_bf16_f32 v15, v2, v3
	v_pk_mul_f32 v[2:3], v[6:7], v[12:13] op_sel_hi:[1,0]
	s_mov_b64 vcc, s[4:5]
	v_div_fixup_f32 v6, v5, v13, 1.0
	v_div_fmas_f32 v5, v18, v26, v30
	v_cvt_pk_bf16_f32 v7, v2, v3
	v_pk_mul_f32 v[2:3], v[8:9], v[6:7] op_sel_hi:[1,0]
	v_div_fixup_f32 v6, v5, v14, 1.0
	v_cvt_pk_bf16_f32 v5, v2, v3
	v_pk_mul_f32 v[2:3], v[10:11], v[6:7] op_sel_hi:[1,0]
	ds_write2_b32 v4, v15, v7 offset1:80
	v_cvt_pk_bf16_f32 v2, v2, v3
	ds_write2_b32 v4, v5, v2 offset0:160 offset1:240
	v_add_u32_e32 v4, 0x500, v4
	s_cbranch_scc1 .LBB0_618
	s_and_b32 s2, s44, 7
	s_lshl_b64 s[0:1], s[38:39], 7
	s_lshl_b32 s3, s2, 15
	s_add_u32 s4, s45, s3
	s_addc_u32 s5, s54, 0
	s_lshr_b32 s3, s26, 2
	s_and_b32 s3, s3, 0x3fffffe0
	v_or_b32_e32 v48, s3, v166
	v_lshlrev_b64 v[0:1], 8, v[48:49]
	v_lshl_add_u64 v[0:1], s[4:5], 0, v[0:1]
	v_mov_b32_e32 v53, v49
	v_lshl_add_u64 v[58:59], v[0:1], 0, v[52:53]
	global_load_dwordx4 v[0:3], v[58:59], off
	global_load_dwordx4 v[40:43], v[58:59], off offset:32
	global_load_dwordx4 v[32:35], v[58:59], off offset:64
	global_load_dwordx4 v[36:39], v[58:59], off offset:96
	global_load_dwordx4 v[44:47], v[58:59], off offset:128
	s_waitcnt lgkmcnt(0)
	s_barrier
	s_lshl_b32 s4, s9, 7
	s_and_b32 s5, s4, 0x80
	v_add_u32_e32 v97, s5, v86
	ds_read_b64_tr_b16 v[4:5], v97
	ds_read_b64_tr_b16 v[6:7], v97 offset:1280
	global_load_dwordx4 v[62:65], v[58:59], off offset:160
	s_or_b32 s4, s5, 64
	v_add_u32_e32 v134, s4, v86
	ds_read_b64_tr_b16 v[60:61], v97 offset:37120
	v_or_b32_e32 v48, s3, v87
	v_mov_b32_e32 v85, v49
	v_mov_b32_e32 v123, v49
	v_mov_b32_e32 v125, v49
	v_mov_b32_e32 v129, v49
	v_lshl_add_u32 v84, s2, 7, v48
	v_or_b32_e32 v122, 1, v48
	v_or_b32_e32 v124, 2, v48
	v_or_b32_e32 v128, 8, v48
	v_mov_b64_e32 v[54:55], s[20:21]
	v_lshl_add_u64 v[132:133], s[0:1], 0, v[48:49]
	s_lshl_b32 s26, s2, 8
	v_lshlrev_b32_e32 v53, 1, v166
	v_mov_b32_e32 v57, v49
	v_or_b32_e32 v56, s5, v53
	v_mov_b32_e32 v127, v49
	v_or_b32_e32 v126, 3, v48
	v_mov_b32_e32 v131, v49
	v_or_b32_e32 v130, 9, v48
	s_waitcnt vmcnt(5) lgkmcnt(1)
	v_mfma_f32_32x32x16_bf16 v[16:31], v[0:3], v[4:7], 0
	ds_read_b64_tr_b16 v[4:5], v134
	ds_read_b64_tr_b16 v[6:7], v134 offset:1280
	ds_read_b64_tr_b16 v[82:83], v134 offset:37120
	ds_read_b64_tr_b16 v[66:67], v97 offset:5120
	ds_read_b64_tr_b16 v[68:69], v97 offset:6400
	ds_read_b64_tr_b16 v[70:71], v97 offset:10240
	ds_read_b64_tr_b16 v[72:73], v97 offset:11520
	global_load_dwordx4 v[98:101], v[58:59], off offset:192
	s_waitcnt lgkmcnt(5)
	v_mfma_f32_32x32x16_bf16 v[0:15], v[0:3], v[4:7], 0
	s_waitcnt vmcnt(5) lgkmcnt(2)
	v_mfma_f32_32x32x16_bf16 v[16:31], v[40:43], v[66:69], v[16:31]
	ds_read_b64_tr_b16 v[66:67], v134 offset:5120
	ds_read_b64_tr_b16 v[68:69], v134 offset:6400
	ds_read_b64_tr_b16 v[74:75], v134 offset:10240
	ds_read_b64_tr_b16 v[76:77], v134 offset:11520
	s_waitcnt lgkmcnt(2)
; #define LAS __attribute__((address_space(3)))
; __device__ __forceinline__ float bf2f(bf16_t v) { return __uint_as_float((unsigned)v << 16); }
; __device__ __forceinline__ bf16_t f2bf(float f) { return (bf16_t)(pk_bf16(f, 0.f) & 0xffffu); }
; __device__ __forceinline__ int crow(int reg, int h) { return (reg & 3) + 8 * (reg >> 2) + 4 * h; }
; #define MFMA32(a, b, c) __builtin_amdgcn_mfma_f32_32x32x16_bf16((a), (b), (c), 0, 0, 0)
; __device__ __forceinline__ void gmlp_unit(LAS unsigned char* lds, const bf16_t* __restrict__ Zb, const bf16_t* __restrict__ wsp, const float* __restrict__ bsp, bf16_t* __restrict__ mix, int chunk, int g) {
;     ...
; #pragma unroll
;     for (int ks = 0; ks < 8; ++ks) {
;         const bf16x8 af = *(const bf16x8*)(ap + 16 * ks);
; #pragma unroll
;         for (int ci = 0; ci < 2; ++ci) {
;             const LAS unsigned char* vp = lds + vlane + (16 * ks) * VS + (cb0 + ci) * 64;
;             const s16x4 lo = tr_read(vp), hi = tr_read(vp + 4 * VS);
;             const bf16x8 vf = __builtin_shufflevector(lo, hi, 0, 1, 2, 3, 4, 5, 6, 7);
;             acc[ci] = MFMA32(af, vf, acc[ci]);
;         }
;     }
; #pragma unroll
;     for (int ci = 0; ci < 2; ++ci)
; #pragma unroll
;         for (int e = 0; e < 16; ++e) {
;             const int p = 32 * pb + crow(e, h), c = 32 * (cb0 + ci) + r;
;             const float u = bf2f(Zb[(row0 + p) * NIN0 + 1088 + g * 128 + c]);
;             mix[(row0 + p) * DM + 1024 + g * 128 + c] = f2bf(u * (acc[ci][e] + bsp[g * 128 + p]));
	v_mfma_f32_32x32x16_bf16 v[0:15], v[40:43], v[66:69], v[0:15]
	ds_read_b64_tr_b16 v[40:41], v97 offset:15360
	ds_read_b64_tr_b16 v[42:43], v97 offset:16640
	ds_read_b64_tr_b16 v[66:67], v97 offset:20480
	ds_read_b64_tr_b16 v[68:69], v97 offset:21760
	ds_read_b64_tr_b16 v[78:79], v97 offset:25600
	ds_read_b64_tr_b16 v[80:81], v97 offset:26880
	ds_read_b64_tr_b16 v[102:103], v97 offset:30720
	ds_read_b64_tr_b16 v[104:105], v97 offset:32000
	s_waitcnt vmcnt(4)
	v_mfma_f32_32x32x16_bf16 v[16:31], v[32:35], v[70:73], v[16:31]
	ds_read_b64_tr_b16 v[70:71], v134 offset:15360
	ds_read_b64_tr_b16 v[72:73], v134 offset:16640
	ds_read_b64_tr_b16 v[106:107], v134 offset:20480
	ds_read_b64_tr_b16 v[108:109], v134 offset:21760
	global_load_dwordx4 v[110:113], v[58:59], off offset:224
	ds_read_b64_tr_b16 v[114:115], v134 offset:25600
	ds_read_b64_tr_b16 v[116:117], v134 offset:26880
	ds_read_b64_tr_b16 v[118:119], v134 offset:30720
	ds_read_b64_tr_b16 v[120:121], v134 offset:32000
	s_waitcnt lgkmcnt(14)
	v_mfma_f32_32x32x16_bf16 v[0:15], v[32:35], v[74:77], v[0:15]
	v_mad_u64_u32 v[32:33], s[2:3], v132, s64, v[54:55]
	v_mad_i32_i24 v33, v133, s64, v33
	v_lshl_add_u64 v[74:75], v[32:33], 0, s[26:27]
	v_lshl_add_u64 v[32:33], v[74:75], 0, v[56:57]
	global_load_ushort v135, v[32:33], off offset:2176
	s_waitcnt vmcnt(5)
	v_mfma_f32_32x32x16_bf16 v[16:31], v[36:39], v[40:43], v[16:31]
	v_lshl_add_u64 v[40:41], v[84:85], 2, s[36:37]
	v_lshl_add_u64 v[42:43], s[0:1], 0, v[122:123]
	v_lshl_add_u64 v[84:85], s[0:1], 0, v[124:125]
	v_lshl_add_u64 v[124:125], s[0:1], 0, v[128:129]
	v_lshl_add_u64 v[122:123], s[0:1], 0, v[126:127]
	v_lshl_add_u64 v[126:127], s[0:1], 0, v[130:131]
	s_waitcnt lgkmcnt(6)
	v_mfma_f32_32x32x16_bf16 v[0:15], v[36:39], v[70:73], v[0:15]
	v_mad_u64_u32 v[36:37], s[2:3], v42, s64, v[54:55]
	v_mad_i32_i24 v37, v43, s64, v37
	v_lshl_add_u64 v[76:77], v[36:37], 0, s[26:27]
	v_lshl_add_u64 v[36:37], v[76:77], 0, v[56:57]
	global_load_ushort v128, v[36:37], off offset:2176
	s_waitcnt vmcnt(5)
	v_mfma_f32_32x32x16_bf16 v[16:31], v[44:47], v[66:69], v[16:31]
	s_waitcnt lgkmcnt(4)
	v_mfma_f32_32x32x16_bf16 v[0:15], v[44:47], v[106:109], v[0:15]
	v_mad_u64_u32 v[44:45], s[2:3], v124, s64, v[54:55]
	v_mad_i32_i24 v45, v125, s64, v45
	v_lshl_add_u64 v[68:69], v[44:45], 0, s[26:27]
	v_lshl_add_u64 v[44:45], v[68:69], 0, v[56:57]
	global_load_ushort v108, v[44:45], off offset:2176
	global_load_dwordx4 v[32:35], v[40:41], off
	v_mad_u64_u32 v[36:37], s[2:3], v84, s64, v[54:55]
	v_mad_i32_i24 v37, v85, s64, v37
	v_lshl_add_u64 v[72:73], v[36:37], 0, s[26:27]
	v_lshl_add_u64 v[36:37], v[72:73], 0, v[56:57]
	global_load_ushort v106, v[36:37], off offset:2176
	v_mad_u64_u32 v[36:37], s[2:3], v122, s64, v[54:55]
	v_mad_i32_i24 v37, v123, s64, v37
	v_lshl_add_u64 v[70:71], v[36:37], 0, s[26:27]
	s_waitcnt vmcnt(7)
	v_mfma_f32_32x32x16_bf16 v[16:31], v[62:65], v[78:81], v[16:31]
	v_lshl_add_u64 v[36:37], v[70:71], 0, v[56:57]
	global_load_ushort v107, v[36:37], off offset:2176
	v_mad_u64_u32 v[44:45], s[2:3], v126, s64, v[54:55]
	global_load_dwordx4 v[36:39], v[40:41], off offset:32
	v_mad_i32_i24 v45, v127, s64, v45
	v_lshl_add_u64 v[66:67], v[44:45], 0, s[26:27]
	v_lshl_add_u64 v[44:45], v[66:67], 0, v[56:57]
	s_waitcnt vmcnt(8)
	v_mfma_f32_32x32x16_bf16 v[16:31], v[98:101], v[102:105], v[16:31]
	global_load_ushort v104, v[44:45], off offset:2176
	ds_read_b64_tr_b16 v[58:59], v97 offset:35840
	ds_read_b64_tr_b16 v[80:81], v134 offset:35840
	v_mov_b32_e32 v45, v49
	v_or_b32_e32 v44, 10, v48
	s_add_u32 s2, s78, s26
	s_addc_u32 s3, s79, 0
	v_mov_b32_e32 v47, v49
	s_waitcnt lgkmcnt(4)
	v_mfma_f32_32x32x16_bf16 v[0:15], v[62:65], v[114:117], v[0:15]
	v_or_b32_e32 v46, 11, v48
	v_lshl_add_u64 v[62:63], s[2:3], 0, v[56:57]
	v_lshlrev_b64 v[64:65], 12, v[42:43]
	s_add_i32 s44, s44, s28
	s_add_i32 s55, s55, s28
	s_cmpk_lt_i32 s44, 0x480
	s_waitcnt lgkmcnt(2)
	v_mfma_f32_32x32x16_bf16 v[0:15], v[98:101], v[118:121], v[0:15]
	v_lshl_add_u64 v[98:99], s[0:1], 0, v[44:45]
	v_mad_u64_u32 v[44:45], s[6:7], v98, s64, v[54:55]
	v_mad_i32_i24 v45, v99, s64, v45
	v_lshl_add_u64 v[78:79], v[44:45], 0, s[26:27]
	v_lshl_add_u64 v[44:45], v[78:79], 0, v[56:57]
	global_load_ushort v97, v[44:45], off offset:2176
	s_waitcnt vmcnt(9) lgkmcnt(1)
	v_mfma_f32_32x32x16_bf16 v[16:31], v[110:113], v[58:61], v[16:31]
	v_lshlrev_b64 v[44:45], 12, v[132:133]
	v_lshl_add_u64 v[100:101], s[0:1], 0, v[46:47]
	s_waitcnt vmcnt(8)
	v_lshlrev_b32_e32 v58, 16, v135
	v_lshl_add_u64 v[46:47], v[62:63], 0, v[44:45]
	v_mov_b32_e32 v59, v49
	v_lshlrev_b64 v[60:61], 12, v[124:125]
	s_waitcnt vmcnt(5)
	s_nop 3
	v_add_f32_e32 v16, v16, v32
	v_mul_f32_e32 v16, v16, v58
	v_cvt_pk_bf16_f32 v16, v16, s0
	v_or_b32_e32 v58, 16, v48
	global_store_short v[46:47], v16, off offset:2048
	v_mad_u64_u32 v[46:47], s[6:7], v100, s64, v[54:55]
	v_lshl_add_u64 v[102:103], s[0:1], 0, v[58:59]
	v_mad_i32_i24 v47, v101, s64, v47
	v_mad_u64_u32 v[58:59], s[6:7], v102, s64, v[54:55]
	s_waitcnt lgkmcnt(0)
	v_mfma_f32_32x32x16_bf16 v[0:15], v[110:113], v[80:83], v[0:15]
	v_lshl_add_u64 v[80:81], v[46:47], 0, s[26:27]
	v_mad_i32_i24 v59, v103, s64, v59
	v_lshl_add_u64 v[46:47], v[80:81], 0, v[56:57]
	v_lshl_add_u64 v[82:83], v[58:59], 0, s[26:27]
	v_lshl_add_u64 v[58:59], v[82:83], 0, v[56:57]
	global_load_ushort v129, v[46:47], off offset:2176
	global_load_ushort v130, v[58:59], off offset:2176
	v_lshlrev_b32_e32 v16, 16, v128
	v_add_f32_e32 v17, v17, v33
	v_mul_f32_e32 v16, v17, v16
	v_cvt_pk_bf16_f32 v46, v16, s0
	v_lshl_add_u64 v[16:17], v[62:63], 0, v[64:65]
	global_store_short v[16:17], v46, off offset:2048
	s_waitcnt vmcnt(8)
; __device__ __forceinline__ float bf2f(bf16_t v) { return __uint_as_float((unsigned)v << 16); }
; __device__ __forceinline__ bf16_t f2bf(float f) { return (bf16_t)(pk_bf16(f, 0.f) & 0xffffu); }
; __device__ __forceinline__ int crow(int reg, int h) { return (reg & 3) + 8 * (reg >> 2) + 4 * h; }
; __device__ __forceinline__ void gmlp_unit(LAS unsigned char* lds, const bf16_t* __restrict__ Zb, const bf16_t* __restrict__ wsp, const float* __restrict__ bsp, bf16_t* __restrict__ mix, int chunk, int g) {
;     ...
; #pragma unroll
;     for (int ci = 0; ci < 2; ++ci)
; #pragma unroll
;         for (int e = 0; e < 16; ++e) {
;             const int p = 32 * pb + crow(e, h), c = 32 * (cb0 + ci) + r;
;             const float u = bf2f(Zb[(row0 + p) * NIN0 + 1088 + g * 128 + c]);
;             mix[(row0 + p) * DM + 1024 + g * 128 + c] = f2bf(u * (acc[ci][e] + bsp[g * 128 + p]));
;         }
	v_lshlrev_b32_e32 v16, 16, v106
	v_add_f32_e32 v17, v18, v34
	v_mul_f32_e32 v16, v17, v16
	v_lshlrev_b64 v[46:47], 12, v[84:85]
	v_cvt_pk_bf16_f32 v18, v16, s0
	v_lshl_add_u64 v[16:17], v[62:63], 0, v[46:47]
	global_store_short v[16:17], v18, off offset:2048
	s_waitcnt vmcnt(8)
	v_lshlrev_b32_e32 v16, 16, v107
	v_add_f32_e32 v17, v19, v35
	v_mul_f32_e32 v16, v17, v16
	v_lshlrev_b64 v[58:59], 12, v[122:123]
	v_cvt_pk_bf16_f32 v18, v16, s0
	v_lshl_add_u64 v[16:17], v[62:63], 0, v[58:59]
	global_store_short v[16:17], v18, off offset:2048
	v_lshlrev_b32_e32 v16, 16, v108
	s_waitcnt vmcnt(8)
	v_add_f32_e32 v17, v20, v36
	v_mul_f32_e32 v16, v17, v16
	v_cvt_pk_bf16_f32 v18, v16, s0
	v_lshl_add_u64 v[16:17], v[62:63], 0, v[60:61]
	global_store_short v[16:17], v18, off offset:2048
	s_waitcnt vmcnt(8)
	v_lshlrev_b32_e32 v16, 16, v104
	v_add_f32_e32 v17, v21, v37
	v_mul_f32_e32 v16, v17, v16
	v_lshlrev_b64 v[20:21], 12, v[126:127]
	v_cvt_pk_bf16_f32 v112, v16, s0
	v_lshl_add_u64 v[42:43], v[62:63], 0, v[20:21]
	v_or_b32_e32 v84, 17, v48
	v_mov_b32_e32 v85, v49
	global_store_short v[42:43], v112, off offset:2048
	v_or_b32_e32 v42, 19, v48
	v_mov_b32_e32 v43, v49
	v_lshl_add_u64 v[104:105], s[0:1], 0, v[84:85]
	v_lshl_add_u64 v[112:113], s[0:1], 0, v[42:43]
	v_mad_u64_u32 v[84:85], s[6:7], v104, s64, v[54:55]
	v_mad_u64_u32 v[42:43], s[6:7], v112, s64, v[54:55]
	v_mad_i32_i24 v85, v105, s64, v85
	v_mad_i32_i24 v43, v113, s64, v43
	global_load_dwordx4 v[16:19], v[40:41], off offset:64
	v_lshl_add_u64 v[106:107], v[84:85], 0, s[26:27]
	v_lshl_add_u64 v[114:115], v[42:43], 0, s[26:27]
	v_lshl_add_u64 v[84:85], v[106:107], 0, v[56:57]
	v_lshl_add_u64 v[42:43], v[114:115], 0, v[56:57]
	global_load_ushort v128, v[84:85], off offset:2176
	global_load_ushort v132, v[42:43], off offset:2176
	v_or_b32_e32 v84, 18, v48
	v_mov_b32_e32 v85, v49
	v_lshl_add_u64 v[108:109], s[0:1], 0, v[84:85]
	v_mad_u64_u32 v[84:85], s[6:7], v108, s64, v[54:55]
	v_mad_i32_i24 v85, v109, s64, v85
	v_lshl_add_u64 v[110:111], v[84:85], 0, s[26:27]
	v_lshl_add_u64 v[84:85], v[110:111], 0, v[56:57]
	global_load_ushort v131, v[84:85], off offset:2176
	v_or_b32_e32 v42, 24, v48
	v_mov_b32_e32 v43, v49
	v_lshl_add_u64 v[116:117], s[0:1], 0, v[42:43]
	v_mad_u64_u32 v[42:43], s[6:7], v116, s64, v[54:55]
	v_or_b32_e32 v84, 25, v48
	v_mov_b32_e32 v85, v49
	v_mad_i32_i24 v43, v117, s64, v43
	v_lshl_add_u64 v[120:121], s[0:1], 0, v[84:85]
	v_lshl_add_u64 v[118:119], v[42:43], 0, s[26:27]
	v_mad_u64_u32 v[84:85], s[6:7], v120, s64, v[54:55]
	v_lshl_add_u64 v[42:43], v[118:119], 0, v[56:57]
	v_mad_i32_i24 v85, v121, s64, v85
	global_load_ushort v133, v[42:43], off offset:2176
	s_nop 0
	global_load_dwordx4 v[40:43], v[40:41], off offset:96
	v_lshl_add_u64 v[122:123], v[84:85], 0, s[26:27]
	v_lshl_add_u64 v[84:85], v[122:123], 0, v[56:57]
	global_load_ushort v134, v[84:85], off offset:2176
	v_or_b32_e32 v84, 26, v48
	v_mov_b32_e32 v85, v49
	v_lshl_add_u64 v[124:125], s[0:1], 0, v[84:85]
	v_mad_u64_u32 v[84:85], s[6:7], v124, s64, v[54:55]
	v_mad_i32_i24 v85, v125, s64, v85
	v_lshl_add_u64 v[126:127], v[84:85], 0, s[26:27]
	s_waitcnt vmcnt(15)
	v_lshlrev_b32_e32 v97, 16, v97
	v_add_f32_e32 v22, v22, v38
	v_lshl_add_u64 v[84:85], v[126:127], 0, v[56:57]
	v_mul_f32_e32 v22, v22, v97
	global_load_ushort v97, v[84:85], off offset:2176
	v_lshlrev_b64 v[84:85], 12, v[98:99]
	v_cvt_pk_bf16_f32 v22, v22, s0
	v_lshl_add_u64 v[98:99], v[62:63], 0, v[84:85]
	v_or_b32_e32 v48, 27, v48
	global_store_short v[98:99], v22, off offset:2048
	v_lshl_add_u64 v[98:99], s[0:1], 0, v[48:49]
	v_mad_u64_u32 v[54:55], s[0:1], v98, s64, v[54:55]
	v_mad_i32_i24 v55, v99, s64, v55
	v_lshl_add_u64 v[54:55], v[54:55], 0, s[26:27]
	v_lshl_add_u64 v[56:57], v[54:55], 0, v[56:57]
	global_load_ushort v135, v[56:57], off offset:2176
	s_waitcnt vmcnt(16)
	v_lshlrev_b32_e32 v22, 16, v129
	v_add_f32_e32 v23, v23, v39
	v_mul_f32_e32 v22, v23, v22
	v_cvt_pk_bf16_f32 v48, v22, s0
	v_lshlrev_b64 v[22:23], 12, v[100:101]
	v_lshl_add_u64 v[56:57], v[62:63], 0, v[22:23]
	global_store_short v[56:57], v48, off offset:2048
	v_or_b32_e32 v48, s4, v53
	v_lshl_add_u64 v[56:57], v[74:75], 0, v[48:49]
	global_load_ushort v53, v[56:57], off offset:2176
	s_waitcnt vmcnt(17)
	v_lshlrev_b32_e32 v100, 16, v130
	v_lshl_add_u64 v[70:71], v[70:71], 0, v[48:49]
	v_lshl_add_u64 v[72:73], v[72:73], 0, v[48:49]
	v_lshl_add_u64 v[66:67], v[66:67], 0, v[48:49]
	v_add_f32_e32 v0, v0, v32
	v_add_f32_e32 v1, v1, v33
	v_lshl_add_u64 v[32:33], v[54:55], 0, v[48:49]
	global_load_ushort v32, v[32:33], off offset:2176
	s_waitcnt vmcnt(12)
	v_add_f32_e32 v24, v24, v16
	v_mul_f32_e32 v24, v24, v100
	global_load_ushort v100, v[70:71], off offset:2176
	v_lshlrev_b64 v[56:57], 12, v[102:103]
	v_cvt_pk_bf16_f32 v24, v24, s0
	v_lshl_add_u64 v[74:75], v[62:63], 0, v[56:57]
	global_store_short v[74:75], v24, off offset:2048
	s_waitcnt vmcnt(13)
	v_lshlrev_b32_e32 v24, 16, v128
	v_lshl_add_u64 v[74:75], v[76:77], 0, v[48:49]
	v_add_f32_e32 v25, v25, v17
	global_load_ushort v76, v[74:75], off offset:2176
	v_mul_f32_e32 v24, v25, v24
	v_cvt_pk_bf16_f32 v77, v24, s0
	v_lshlrev_b64 v[24:25], 12, v[104:105]
	v_lshl_add_u64 v[74:75], v[62:63], 0, v[24:25]
	global_store_short v[74:75], v77, off offset:2048
	global_load_ushort v77, v[72:73], off offset:2176
	s_waitcnt vmcnt(14)
	v_lshlrev_b32_e32 v74, 16, v131
	v_add_f32_e32 v26, v26, v18
	v_mul_f32_e32 v26, v26, v74
	global_load_ushort v102, v[66:67], off offset:2176
	v_lshlrev_b64 v[72:73], 12, v[108:109]
	v_cvt_pk_bf16_f32 v26, v26, s0
	v_lshl_add_u64 v[74:75], v[62:63], 0, v[72:73]
	global_store_short v[74:75], v26, off offset:2048
	v_lshlrev_b32_e32 v26, 16, v132
	v_add_f32_e32 v27, v27, v19
	v_mul_f32_e32 v70, v27, v26
	v_lshl_add_u64 v[26:27], v[68:69], 0, v[48:49]
	global_load_ushort v101, v[26:27], off offset:2176
	s_waitcnt vmcnt(16)
; __device__ __forceinline__ float bf2f(bf16_t v) { return __uint_as_float((unsigned)v << 16); }
; __device__ __forceinline__ bf16_t f2bf(float f) { return (bf16_t)(pk_bf16(f, 0.f) & 0xffffu); }
; __device__ __forceinline__ int crow(int reg, int h) { return (reg & 3) + 8 * (reg >> 2) + 4 * h; }
; __device__ __forceinline__ void gmlp_unit(LAS unsigned char* lds, const bf16_t* __restrict__ Zb, const bf16_t* __restrict__ wsp, const float* __restrict__ bsp, bf16_t* __restrict__ mix, int chunk, int g) {
;     ...
; #pragma unroll
;     for (int ci = 0; ci < 2; ++ci)
; #pragma unroll
;         for (int e = 0; e < 16; ++e) {
;             const int p = 32 * pb + crow(e, h), c = 32 * (cb0 + ci) + r;
;             const float u = bf2f(Zb[(row0 + p) * NIN0 + 1088 + g * 128 + c]);
;             mix[(row0 + p) * DM + 1024 + g * 128 + c] = f2bf(u * (acc[ci][e] + bsp[g * 128 + p]));
;         }
;     __syncthreads();
; __global__ void __launch_bounds__(512, 2) mk_fwd(Args args) {
;     ...
;         for (int j = (F.vcu + F.G - 64) % F.G; j < 1152; j += F.G) gmlp_unit(F.lds, Zb, (const bf16_t*)(ws + WS_WSP), args.in[16], MIXb, j >> 3, j & 7);
	v_lshlrev_b32_e32 v66, 16, v133
	s_waitcnt vmcnt(15)
	v_add_f32_e32 v28, v28, v40
	v_lshlrev_b64 v[26:27], 12, v[112:113]
	v_mul_f32_e32 v28, v28, v66
	v_lshl_add_u64 v[66:67], v[78:79], 0, v[48:49]
	v_lshl_add_u64 v[74:75], v[110:111], 0, v[48:49]
	v_cvt_pk_bf16_f32 v70, v70, s0
	v_lshl_add_u64 v[68:69], v[62:63], 0, v[26:27]
	global_load_ushort v78, v[66:67], off offset:2176
	v_cvt_pk_bf16_f32 v28, v28, s0
	global_load_ushort v74, v[74:75], off offset:2176
	v_lshlrev_b64 v[66:67], 12, v[116:117]
	global_store_short v[68:69], v70, off offset:2048
	v_lshl_add_u64 v[68:69], v[62:63], 0, v[66:67]
	global_store_short v[68:69], v28, off offset:2048
	v_lshl_add_u64 v[68:69], v[80:81], 0, v[48:49]
	global_load_ushort v79, v[68:69], off offset:2176
	s_waitcnt vmcnt(19)
	v_lshlrev_b32_e32 v28, 16, v134
	v_add_f32_e32 v29, v29, v41
	v_mul_f32_e32 v28, v29, v28
	v_lshl_add_u64 v[68:69], v[82:83], 0, v[48:49]
	v_cvt_pk_bf16_f32 v70, v28, s0
	v_lshlrev_b64 v[28:29], 12, v[120:121]
	global_load_ushort v80, v[68:69], off offset:2176
	v_lshl_add_u64 v[68:69], v[62:63], 0, v[28:29]
	global_store_short v[68:69], v70, off offset:2048
	v_lshl_add_u64 v[68:69], v[106:107], 0, v[48:49]
	global_load_ushort v81, v[68:69], off offset:2176
	s_waitcnt vmcnt(21)
	v_lshlrev_b32_e32 v70, 16, v97
	v_add_f32_e32 v30, v30, v42
	v_mul_f32_e32 v30, v30, v70
	v_lshlrev_b64 v[68:69], 12, v[124:125]
	v_cvt_pk_bf16_f32 v30, v30, s0
	v_lshl_add_u64 v[70:71], v[62:63], 0, v[68:69]
	global_store_short v[70:71], v30, off offset:2048
	s_waitcnt vmcnt(20)
	v_lshlrev_b32_e32 v30, 16, v135
	v_add_f32_e32 v31, v31, v43
	v_mul_f32_e32 v70, v31, v30
	v_lshl_add_u64 v[30:31], v[114:115], 0, v[48:49]
	global_load_ushort v75, v[30:31], off offset:2176
	v_lshlrev_b64 v[30:31], 12, v[98:99]
	v_cvt_pk_bf16_f32 v70, v70, s0
	v_lshl_add_u64 v[62:63], v[62:63], 0, v[30:31]
	global_store_short v[62:63], v70, off offset:2048
	v_lshl_add_u64 v[62:63], v[118:119], 0, v[48:49]
	global_load_ushort v82, v[62:63], off offset:2176
	s_waitcnt vmcnt(21)
	v_lshlrev_b32_e32 v53, 16, v53
	v_lshl_add_u64 v[70:71], v[122:123], 0, v[48:49]
	v_lshl_add_u64 v[62:63], s[2:3], 0, v[48:49]
	v_mul_f32_e32 v0, v0, v53
	global_load_ushort v53, v[70:71], off offset:2176
	v_cvt_pk_bf16_f32 v0, v0, s0
	v_lshl_add_u64 v[44:45], v[62:63], 0, v[44:45]
	global_store_short v[44:45], v0, off offset:2048
	v_lshl_add_u64 v[44:45], v[126:127], 0, v[48:49]
	global_load_ushort v44, v[44:45], off offset:2176
	s_waitcnt vmcnt(20)
	v_lshlrev_b32_e32 v0, 16, v76
	v_mul_f32_e32 v0, v1, v0
	v_cvt_pk_bf16_f32 v45, v0, s0
	v_lshl_add_u64 v[0:1], v[62:63], 0, v[64:65]
	global_store_short v[0:1], v45, off offset:2048
	v_add_f32_e32 v1, v2, v34
	s_waitcnt vmcnt(19)
	v_lshlrev_b32_e32 v0, 16, v77
	v_mul_f32_e32 v0, v1, v0
	v_cvt_pk_bf16_f32 v2, v0, s0
	v_lshl_add_u64 v[0:1], v[62:63], 0, v[46:47]
	global_store_short v[0:1], v2, off offset:2048
	v_lshlrev_b32_e32 v0, 16, v100
	v_add_f32_e32 v1, v3, v35
	v_mul_f32_e32 v0, v1, v0
	v_cvt_pk_bf16_f32 v2, v0, s0
	v_lshl_add_u64 v[0:1], v[62:63], 0, v[58:59]
	global_store_short v[0:1], v2, off offset:2048
	v_add_f32_e32 v1, v4, v36
	s_waitcnt vmcnt(18)
	v_lshlrev_b32_e32 v0, 16, v101
	v_mul_f32_e32 v0, v1, v0
	v_cvt_pk_bf16_f32 v2, v0, s0
	v_lshl_add_u64 v[0:1], v[62:63], 0, v[60:61]
	global_store_short v[0:1], v2, off offset:2048
	v_lshlrev_b32_e32 v0, 16, v102
	v_add_f32_e32 v1, v5, v37
	v_mul_f32_e32 v0, v1, v0
	v_cvt_pk_bf16_f32 v2, v0, s0
	v_lshl_add_u64 v[0:1], v[62:63], 0, v[20:21]
	global_store_short v[0:1], v2, off offset:2048
	s_waitcnt vmcnt(19)
	v_lshlrev_b32_e32 v0, 16, v78
	v_add_f32_e32 v1, v6, v38
	v_mul_f32_e32 v0, v1, v0
	v_cvt_pk_bf16_f32 v2, v0, s0
	v_lshl_add_u64 v[0:1], v[62:63], 0, v[84:85]
	global_store_short v[0:1], v2, off offset:2048
	s_waitcnt vmcnt(16)
	v_lshlrev_b32_e32 v0, 16, v79
	v_add_f32_e32 v1, v7, v39
	v_mul_f32_e32 v0, v1, v0
	v_cvt_pk_bf16_f32 v2, v0, s0
	v_lshl_add_u64 v[0:1], v[62:63], 0, v[22:23]
	global_store_short v[0:1], v2, off offset:2048
	v_add_f32_e32 v1, v8, v16
	s_waitcnt vmcnt(16)
	v_lshlrev_b32_e32 v0, 16, v80
	v_mul_f32_e32 v0, v1, v0
	v_cvt_pk_bf16_f32 v2, v0, s0
	v_lshl_add_u64 v[0:1], v[62:63], 0, v[56:57]
	global_store_short v[0:1], v2, off offset:2048
	s_waitcnt vmcnt(15)
	v_lshlrev_b32_e32 v0, 16, v81
	v_add_f32_e32 v1, v9, v17
	v_mul_f32_e32 v0, v1, v0
	v_cvt_pk_bf16_f32 v2, v0, s0
	v_lshl_add_u64 v[0:1], v[62:63], 0, v[24:25]
	global_store_short v[0:1], v2, off offset:2048
	v_lshlrev_b32_e32 v0, 16, v74
	v_add_f32_e32 v1, v10, v18
	v_mul_f32_e32 v0, v1, v0
	v_cvt_pk_bf16_f32 v2, v0, s0
	v_lshl_add_u64 v[0:1], v[62:63], 0, v[72:73]
	global_store_short v[0:1], v2, off offset:2048
	s_waitcnt vmcnt(15)
	v_lshlrev_b32_e32 v0, 16, v75
	v_add_f32_e32 v1, v11, v19
	v_mul_f32_e32 v0, v1, v0
	v_cvt_pk_bf16_f32 v2, v0, s0
	v_lshl_add_u64 v[0:1], v[62:63], 0, v[26:27]
	global_store_short v[0:1], v2, off offset:2048
	s_waitcnt vmcnt(14)
	v_lshlrev_b32_e32 v0, 16, v82
	v_add_f32_e32 v1, v12, v40
	v_mul_f32_e32 v0, v1, v0
	v_cvt_pk_bf16_f32 v2, v0, s0
	v_lshl_add_u64 v[0:1], v[62:63], 0, v[66:67]
	global_store_short v[0:1], v2, off offset:2048
	s_waitcnt vmcnt(14)
	v_lshlrev_b32_e32 v0, 16, v53
	v_add_f32_e32 v1, v13, v41
	v_mul_f32_e32 v0, v1, v0
	v_cvt_pk_bf16_f32 v2, v0, s0
	v_lshl_add_u64 v[0:1], v[62:63], 0, v[28:29]
	global_store_short v[0:1], v2, off offset:2048
	s_waitcnt vmcnt(13)
	v_lshlrev_b32_e32 v0, 16, v44
	v_add_f32_e32 v1, v14, v42
	v_mul_f32_e32 v0, v1, v0
	v_cvt_pk_bf16_f32 v2, v0, s0
	v_lshl_add_u64 v[0:1], v[62:63], 0, v[68:69]
	global_store_short v[0:1], v2, off offset:2048
	v_lshlrev_b32_e32 v0, 16, v32
	v_add_f32_e32 v1, v15, v43
	v_mul_f32_e32 v0, v1, v0
	v_cvt_pk_bf16_f32 v2, v0, s0
	v_lshl_add_u64 v[0:1], v[62:63], 0, v[30:31]
	global_store_short v[0:1], v2, off offset:2048
	s_barrier
	s_cbranch_scc1 .LBB0_617
